# on top of v60: SiLU in the PAIR epilogue uses packed f32 mul (exp2 prescale) and packed add (+1), 64 fewer VALU per wave per tile, same arithmetic
# baseline (speedup 1.0000x reference)
.LBB0_453:
	s_andn2_b64 vcc, exec, s[0:1]
	s_cbranch_vccnz .LBB0_509
	s_mov_b32 s100, 0xbfb8aa3b
	s_mov_b32 s101, 0xbfb8aa3b
	v_ashrrev_i32_e32 v2, 31, v196
	v_lshrrev_b32_e32 v2, 26, v2
	v_add_u32_e32 v2, v196, v2
	v_ashrrev_i32_e32 v6, 6, v2
	v_bfe_i32 v2, v196, 27, 1
	v_lshlrev_b32_e32 v1, 4, v196
	v_lshrrev_b32_e32 v2, 22, v2
	v_add_u32_e32 v2, v1, v2
	v_and_b32_e32 v2, 0xfffffc00, v2
	v_sub_u32_e32 v2, v1, v2
	v_lshrrev_b32_e32 v3, 4, v2
	s_and_b64 s[0:1], s[4:5], exec
	v_bitop3_b32 v2, v3, v2, 32 bitop3:0x6c
	s_mov_b32 s0, 0x1c00000
	v_ashrrev_i32_e32 v4, 31, v2
	s_cselect_b32 s10, 0x2d00000, s0
	v_readlane_b32 s0, v255, 49
	v_lshrrev_b32_e32 v4, 26, v4
	s_cmp_lt_u32 s0, 64
	v_add_u32_e32 v4, v2, v4
	s_cselect_b64 s[14:15], -1, 0
	v_lshlrev_b32_e32 v3, 3, v6
	v_ashrrev_i32_e32 v7, 6, v4
	v_and_b32_e32 v4, 0xc0, v4
	s_and_b64 s[0:1], s[14:15], exec
	v_and_b32_e32 v3, -16, v3
	v_sub_u32_e32 v2, v2, v4
	s_cselect_b32 s0, 0xb00000, s10
	v_readlane_b32 s10, v255, 50
	v_add_u32_e32 v3, v7, v3
	v_ashrrev_i16_sdwa v2, v226, sext(v2) dst_sel:DWORD dst_unused:UNUSED_PAD src0_sel:DWORD src1_sel:BYTE_0
	s_add_u32 s13, s10, s0
	v_lshlrev_b32_e32 v5, 5, v6
	s_waitcnt lgkmcnt(1)
	v_bfe_i32 v8, v2, 0, 16
	v_lshlrev_b32_e32 v2, 1, v3
	v_lshrrev_b32_e32 v4, 2, v3
	v_and_b32_e32 v9, 3, v7
	s_mov_b32 s0, 0x1fffe0
	v_and_b32_e32 v5, 32, v5
	v_and_b32_e32 v2, 24, v2
	v_and_b32_e32 v4, 4, v4
	v_and_or_b32 v9, v3, s0, v9
	v_or3_b32 v2, v9, v4, v2
	v_add_lshl_u32 v4, v5, v8, 1
	v_add_u32_e32 v1, 0x2000, v1
	v_lshl_add_u32 v148, v2, 11, v4
	v_ashrrev_i32_e32 v2, 31, v1
	v_lshrrev_b32_e32 v2, 22, v2
	v_add_u32_e32 v2, v1, v2
	v_ashrrev_i32_e32 v9, 10, v2
	v_mul_i32_i24_e32 v2, 0x400, v9
	v_sub_u32_e32 v1, v1, v2
	v_lshrrev_b32_e32 v2, 4, v1
	v_bitop3_b32 v1, v2, v1, 32 bitop3:0x6c
	v_lshl_add_u32 v146, v3, 7, v4
	v_ashrrev_i32_e32 v3, 31, v1
	v_lshrrev_b32_e32 v3, 26, v3
	v_lshlrev_b32_e32 v2, 3, v9
	v_add_u32_e32 v3, v1, v3
	v_readlane_b32 s11, v255, 51
	v_and_b32_e32 v2, -16, v2
	s_waitcnt lgkmcnt(0)
	v_ashrrev_i32_e32 v10, 6, v3
	s_addc_u32 s21, s11, 0
	s_ashr_i32 s16, s9, 6
	v_add_u32_e32 v2, v10, v2
	v_and_b32_e32 v3, 0xc0, v3
	v_and_b32_e32 v5, 3, v10
	s_ashr_i32 s47, s46, 31
	s_ashr_i32 s43, s42, 31
	v_sub_u32_e32 v1, v1, v3
	v_and_or_b32 v5, v2, s0, v5
	s_ashr_i32 s17, s9, 8
	s_lshl_b32 s28, s16, 10
	s_lshl_b64 s[10:11], s[46:47], 19
	s_lshl_b64 s[0:1], s[42:43], 19
	v_ashrrev_i16_sdwa v1, v226, sext(v1) dst_sel:DWORD dst_unused:UNUSED_PAD src0_sel:DWORD src1_sel:BYTE_0
	s_add_u32 s0, s13, s0
	v_lshlrev_b32_e32 v4, 5, v9
	v_bfe_i32 v11, v1, 0, 16
	v_lshlrev_b32_e32 v1, 1, v2
	v_lshrrev_b32_e32 v3, 2, v2
	s_addc_u32 s1, s21, s1
	s_add_i32 s29, s28, 0
	v_and_b32_e32 v4, 32, v4
	v_and_b32_e32 v1, 24, v1
	v_and_b32_e32 v3, 4, v3
	s_add_i32 m0, s29, 0x10000
	v_or3_b32 v1, v5, v3, v1
	v_add_lshl_u32 v3, v4, v11, 1
	global_load_lds_dwordx4 v148, s[0:1]
	s_add_i32 m0, s29, 0x12000
	v_lshl_add_u32 v152, v1, 11, v3
	s_add_u32 s18, s0, 0x40000
	global_load_lds_dwordx4 v152, s[0:1]
	s_addc_u32 s19, s1, 0
	s_add_i32 m0, s29, 0x14000
	v_lshl_add_u32 v150, v2, 7, v3
	global_load_lds_dwordx4 v148, s[18:19]
	s_add_i32 m0, s29, 0x16000
	s_add_u32 s50, s58, s10
	s_addc_u32 s51, s59, s11
	s_add_i32 s31, s29, 0x2000
	global_load_lds_dwordx4 v152, s[18:19]
	s_mov_b32 m0, s29
	s_add_u32 s10, s50, 0x4000
	global_load_lds_dwordx4 v146, s[50:51]
	s_mov_b32 m0, s31
	s_addc_u32 s11, s51, 0
	s_add_i32 s33, s29, 0x4000
	global_load_lds_dwordx4 v150, s[50:51]
	s_mov_b32 m0, s33
	s_add_i32 s36, s29, 0x6000
	global_load_lds_dwordx4 v146, s[10:11]
	s_mov_b32 m0, s36
	v_mov_b32_e32 v149, v191
	global_load_lds_dwordx4 v150, s[10:11]
	v_mov_b32_e32 v153, v191
	s_cmp_eq_u32 s17, 1
	s_mov_b32 s57, s72
	v_lshl_add_u64 v[2:3], s[0:1], 0, v[148:149]
	s_cselect_b64 s[10:11], -1, 0
	s_cmp_lg_u32 s17, 1
	v_lshl_add_u64 v[4:5], s[0:1], 0, v[152:153]
	s_cbranch_scc1 .LBB0_456
	s_barrier

.LBB0_473:
	v_pk_fma_f32 v[144:145], v[144:145], v[182:183], v[96:97] op_sel_hi:[1,0,1]
	v_pk_fma_f32 v[142:143], v[142:143], v[182:183], v[94:95] op_sel_hi:[1,0,1]
	v_pk_fma_f32 v[140:141], v[140:141], v[182:183], v[92:93] op_sel_hi:[1,0,1]
	v_pk_fma_f32 v[138:139], v[138:139], v[182:183], v[90:91] op_sel_hi:[1,0,1]
	v_pk_fma_f32 v[186:187], v[136:137], v[182:183], v[88:89] op_sel_hi:[1,0,1]
	v_pk_fma_f32 v[188:189], v[134:135], v[182:183], v[86:87] op_sel_hi:[1,0,1]
	v_pk_fma_f32 v[184:185], v[132:133], v[182:183], v[84:85] op_sel_hi:[1,0,1]
	v_pk_fma_f32 v[182:183], v[130:131], v[182:183], v[82:83] op_sel_hi:[1,0,1]
	s_and_b64 vcc, exec, s[0:1]
	s_mov_b64 s[0:1], -1
	s_cbranch_vccnz .LBB0_475
	v_pk_mul_f32 v[130:131], v[142:143], s[100:101]
	v_pk_mul_f32 v[134:135], v[138:139], s[100:101]
	v_pk_mul_f32 v[132:133], v[144:145], s[100:101]
	v_pk_mul_f32 v[136:137], v[140:141], s[100:101]
	v_exp_f32_e32 v130, v130
	v_exp_f32_e32 v131, v131
	v_exp_f32_e32 v134, v134
	v_exp_f32_e32 v135, v135
	v_exp_f32_e32 v132, v132
	v_exp_f32_e32 v133, v133
	v_exp_f32_e32 v136, v136
	v_exp_f32_e32 v137, v137
	v_pk_add_f32 v[130:131], v[130:131], 1.0 op_sel_hi:[1,0]
	v_pk_add_f32 v[134:135], v[134:135], 1.0 op_sel_hi:[1,0]
	v_pk_add_f32 v[132:133], v[132:133], 1.0 op_sel_hi:[1,0]
	v_pk_add_f32 v[136:137], v[136:137], 1.0 op_sel_hi:[1,0]
	v_rcp_f32_e32 v130, v130
	v_rcp_f32_e32 v131, v131
	v_rcp_f32_e32 v134, v134
	v_rcp_f32_e32 v135, v135
	v_rcp_f32_e32 v132, v132
	v_rcp_f32_e32 v133, v133
	v_rcp_f32_e32 v136, v136
	v_rcp_f32_e32 v137, v137
	v_pk_mul_f32 v[130:131], v[142:143], v[130:131]
	v_pk_mul_f32 v[134:135], v[138:139], v[134:135]
	v_pk_mul_f32 v[132:133], v[144:145], v[132:133]
	v_pk_mul_f32 v[136:137], v[140:141], v[136:137]
	v_pk_mul_f32 v[132:133], v[186:187], v[132:133]
	v_pk_mul_f32 v[130:131], v[188:189], v[130:131]
	v_pk_mul_f32 v[136:137], v[184:185], v[136:137]
	v_pk_mul_f32 v[134:135], v[182:183], v[134:135]
	s_mov_b64 s[0:1], 0

.LBB0_477:
	v_subrev_u32_e32 v138, s17, v178
	v_cvt_pk_bf16_f32 v130, v130, v131
	v_cvt_pk_bf16_f32 v131, v132, v133
	v_cvt_pk_bf16_f32 v132, v134, v135
	v_mad_i64_i32 v[134:135], s[0:1], s46, v138, 0
	v_cvt_pk_bf16_f32 v133, v136, v137
	v_lshl_add_u64 v[134:135], v[134:135], 1, v[168:169]
	global_store_dwordx4 v[134:135], v[130:133], off
	v_pk_fma_f32 v[128:129], v[128:129], v[180:181], v[96:97] op_sel_hi:[1,0,1]
	v_pk_fma_f32 v[126:127], v[126:127], v[180:181], v[94:95] op_sel_hi:[1,0,1]
	v_pk_fma_f32 v[124:125], v[124:125], v[180:181], v[92:93] op_sel_hi:[1,0,1]
	v_pk_fma_f32 v[122:123], v[122:123], v[180:181], v[90:91] op_sel_hi:[1,0,1]
	v_pk_fma_f32 v[134:135], v[120:121], v[180:181], v[88:89] op_sel_hi:[1,0,1]
	v_pk_fma_f32 v[136:137], v[118:119], v[180:181], v[86:87] op_sel_hi:[1,0,1]
	v_pk_fma_f32 v[130:131], v[116:117], v[180:181], v[84:85] op_sel_hi:[1,0,1]
	v_pk_fma_f32 v[132:133], v[114:115], v[180:181], v[82:83] op_sel_hi:[1,0,1]
	s_mov_b64 s[0:1], -1
	s_and_b64 vcc, exec, s[6:7]
	s_cbranch_vccz .LBB0_479
	v_pk_mul_f32 v[114:115], v[126:127], s[100:101]
	v_pk_mul_f32 v[118:119], v[122:123], s[100:101]
	v_pk_mul_f32 v[116:117], v[128:129], s[100:101]
	v_pk_mul_f32 v[120:121], v[124:125], s[100:101]
	v_exp_f32_e32 v114, v114
	v_exp_f32_e32 v115, v115
	v_exp_f32_e32 v118, v118
	v_exp_f32_e32 v119, v119
	v_exp_f32_e32 v116, v116
	v_exp_f32_e32 v117, v117
	v_exp_f32_e32 v120, v120
	v_exp_f32_e32 v121, v121
	v_pk_add_f32 v[114:115], v[114:115], 1.0 op_sel_hi:[1,0]
	v_pk_add_f32 v[118:119], v[118:119], 1.0 op_sel_hi:[1,0]
	v_pk_add_f32 v[116:117], v[116:117], 1.0 op_sel_hi:[1,0]
	v_pk_add_f32 v[120:121], v[120:121], 1.0 op_sel_hi:[1,0]
	v_rcp_f32_e32 v114, v114
	v_rcp_f32_e32 v115, v115
	v_rcp_f32_e32 v118, v118
	v_rcp_f32_e32 v119, v119
	v_rcp_f32_e32 v116, v116
	v_rcp_f32_e32 v117, v117
	v_rcp_f32_e32 v120, v120
	v_rcp_f32_e32 v121, v121
	v_pk_mul_f32 v[114:115], v[126:127], v[114:115]
	v_pk_mul_f32 v[118:119], v[122:123], v[118:119]
	v_pk_mul_f32 v[116:117], v[128:129], v[116:117]
	v_pk_mul_f32 v[120:121], v[124:125], v[120:121]
	v_pk_mul_f32 v[116:117], v[134:135], v[116:117]
	v_pk_mul_f32 v[114:115], v[136:137], v[114:115]
	v_pk_mul_f32 v[120:121], v[130:131], v[120:121]
	v_pk_mul_f32 v[118:119], v[132:133], v[118:119]
	s_mov_b64 s[0:1], 0

.LBB0_481:
	v_cvt_pk_bf16_f32 v114, v114, v115
	v_cvt_pk_bf16_f32 v115, v116, v117
	s_nop 0
	v_cvt_pk_bf16_f32 v116, v118, v119
	v_or_b32_e32 v118, 16, v138
	v_mad_i64_i32 v[118:119], s[0:1], s46, v118, 0
	v_cvt_pk_bf16_f32 v117, v120, v121
	v_lshl_add_u64 v[118:119], v[118:119], 1, v[168:169]
	global_store_dwordx4 v[118:119], v[114:117], off
	v_pk_fma_f32 v[112:113], v[112:113], v[176:177], v[96:97] op_sel_hi:[1,0,1]
	v_pk_fma_f32 v[110:111], v[110:111], v[176:177], v[94:95] op_sel_hi:[1,0,1]
	v_pk_fma_f32 v[108:109], v[108:109], v[176:177], v[92:93] op_sel_hi:[1,0,1]
	v_pk_fma_f32 v[106:107], v[106:107], v[176:177], v[90:91] op_sel_hi:[1,0,1]
	v_pk_fma_f32 v[118:119], v[104:105], v[176:177], v[88:89] op_sel_hi:[1,0,1]
	v_pk_fma_f32 v[120:121], v[102:103], v[176:177], v[86:87] op_sel_hi:[1,0,1]
	v_pk_fma_f32 v[114:115], v[100:101], v[176:177], v[84:85] op_sel_hi:[1,0,1]
	v_pk_fma_f32 v[116:117], v[98:99], v[176:177], v[82:83] op_sel_hi:[1,0,1]
	s_mov_b64 s[0:1], -1
	s_and_b64 vcc, exec, s[6:7]
	s_cbranch_vccz .LBB0_483
	v_pk_mul_f32 v[98:99], v[110:111], s[100:101]
	v_pk_mul_f32 v[102:103], v[106:107], s[100:101]
	v_pk_mul_f32 v[100:101], v[112:113], s[100:101]
	v_pk_mul_f32 v[104:105], v[108:109], s[100:101]
	v_exp_f32_e32 v98, v98
	v_exp_f32_e32 v99, v99
	v_exp_f32_e32 v102, v102
	v_exp_f32_e32 v103, v103
	v_exp_f32_e32 v100, v100
	v_exp_f32_e32 v101, v101
	v_exp_f32_e32 v104, v104
	v_exp_f32_e32 v105, v105
	v_pk_add_f32 v[98:99], v[98:99], 1.0 op_sel_hi:[1,0]
	v_pk_add_f32 v[102:103], v[102:103], 1.0 op_sel_hi:[1,0]
	v_pk_add_f32 v[100:101], v[100:101], 1.0 op_sel_hi:[1,0]
	v_pk_add_f32 v[104:105], v[104:105], 1.0 op_sel_hi:[1,0]
	v_rcp_f32_e32 v98, v98
	v_rcp_f32_e32 v99, v99
	v_rcp_f32_e32 v102, v102
	v_rcp_f32_e32 v103, v103
	v_rcp_f32_e32 v100, v100
	v_rcp_f32_e32 v101, v101
	v_rcp_f32_e32 v104, v104
	v_rcp_f32_e32 v105, v105
	v_pk_mul_f32 v[98:99], v[110:111], v[98:99]
	v_pk_mul_f32 v[102:103], v[106:107], v[102:103]
	v_pk_mul_f32 v[100:101], v[112:113], v[100:101]
	v_pk_mul_f32 v[104:105], v[108:109], v[104:105]
	v_pk_mul_f32 v[100:101], v[118:119], v[100:101]
	v_pk_mul_f32 v[98:99], v[120:121], v[98:99]
	v_pk_mul_f32 v[104:105], v[114:115], v[104:105]
	v_pk_mul_f32 v[102:103], v[116:117], v[102:103]
	s_mov_b64 s[0:1], 0

.LBB0_485:
	v_cvt_pk_bf16_f32 v98, v98, v99
	v_cvt_pk_bf16_f32 v99, v100, v101
	s_nop 0
	v_cvt_pk_bf16_f32 v100, v102, v103
	v_or_b32_e32 v102, 32, v138
	v_mad_i64_i32 v[102:103], s[0:1], s46, v102, 0
	v_cvt_pk_bf16_f32 v101, v104, v105
	v_lshl_add_u64 v[102:103], v[102:103], 1, v[168:169]
	global_store_dwordx4 v[102:103], v[98:101], off
	v_pk_fma_f32 v[80:81], v[80:81], v[174:175], v[96:97] op_sel_hi:[1,0,1]
	v_pk_fma_f32 v[78:79], v[78:79], v[174:175], v[94:95] op_sel_hi:[1,0,1]
	v_pk_fma_f32 v[76:77], v[76:77], v[174:175], v[92:93] op_sel_hi:[1,0,1]
	v_pk_fma_f32 v[74:75], v[74:75], v[174:175], v[90:91] op_sel_hi:[1,0,1]
	v_pk_fma_f32 v[102:103], v[72:73], v[174:175], v[88:89] op_sel_hi:[1,0,1]
	v_pk_fma_f32 v[104:105], v[70:71], v[174:175], v[86:87] op_sel_hi:[1,0,1]
	v_pk_fma_f32 v[98:99], v[68:69], v[174:175], v[84:85] op_sel_hi:[1,0,1]
	v_pk_fma_f32 v[100:101], v[66:67], v[174:175], v[82:83] op_sel_hi:[1,0,1]
	s_mov_b64 s[0:1], -1
	s_and_b64 vcc, exec, s[6:7]
	s_cbranch_vccz .LBB0_487
	v_pk_mul_f32 v[66:67], v[78:79], s[100:101]
	v_pk_mul_f32 v[70:71], v[74:75], s[100:101]
	v_pk_mul_f32 v[68:69], v[80:81], s[100:101]
	v_pk_mul_f32 v[72:73], v[76:77], s[100:101]
	v_exp_f32_e32 v66, v66
	v_exp_f32_e32 v67, v67
	v_exp_f32_e32 v70, v70
	v_exp_f32_e32 v71, v71
	v_exp_f32_e32 v68, v68
	v_exp_f32_e32 v69, v69
	v_exp_f32_e32 v72, v72
	v_exp_f32_e32 v73, v73
	v_pk_add_f32 v[66:67], v[66:67], 1.0 op_sel_hi:[1,0]
	v_pk_add_f32 v[70:71], v[70:71], 1.0 op_sel_hi:[1,0]
	v_pk_add_f32 v[68:69], v[68:69], 1.0 op_sel_hi:[1,0]
	v_pk_add_f32 v[72:73], v[72:73], 1.0 op_sel_hi:[1,0]
	v_rcp_f32_e32 v66, v66
	v_rcp_f32_e32 v67, v67
	v_rcp_f32_e32 v70, v70
	v_rcp_f32_e32 v71, v71
	v_rcp_f32_e32 v68, v68
	v_rcp_f32_e32 v69, v69
	v_rcp_f32_e32 v72, v72
	v_rcp_f32_e32 v73, v73
	v_pk_mul_f32 v[66:67], v[78:79], v[66:67]
	v_pk_mul_f32 v[70:71], v[74:75], v[70:71]
	v_pk_mul_f32 v[68:69], v[80:81], v[68:69]
	v_pk_mul_f32 v[72:73], v[76:77], v[72:73]
	v_pk_mul_f32 v[68:69], v[102:103], v[68:69]
	v_pk_mul_f32 v[66:67], v[104:105], v[66:67]
	v_pk_mul_f32 v[72:73], v[98:99], v[72:73]
	v_pk_mul_f32 v[70:71], v[100:101], v[70:71]
	s_mov_b64 s[0:1], 0

.LBB0_489:
	v_cvt_pk_bf16_f32 v66, v66, v67
	v_cvt_pk_bf16_f32 v67, v68, v69
	s_nop 0
	v_cvt_pk_bf16_f32 v68, v70, v71
	v_or_b32_e32 v70, 48, v138
	v_mad_i64_i32 v[70:71], s[0:1], s46, v70, 0
	v_cvt_pk_bf16_f32 v69, v72, v73
	v_lshl_add_u64 v[70:71], v[70:71], 1, v[168:169]
	global_store_dwordx4 v[70:71], v[66:69], off
	v_pk_fma_f32 v[64:65], v[64:65], v[172:173], v[96:97] op_sel_hi:[1,0,1]
	v_pk_fma_f32 v[62:63], v[62:63], v[172:173], v[94:95] op_sel_hi:[1,0,1]
	v_pk_fma_f32 v[60:61], v[60:61], v[172:173], v[92:93] op_sel_hi:[1,0,1]
	v_pk_fma_f32 v[58:59], v[58:59], v[172:173], v[90:91] op_sel_hi:[1,0,1]
	v_pk_fma_f32 v[70:71], v[56:57], v[172:173], v[88:89] op_sel_hi:[1,0,1]
	v_pk_fma_f32 v[72:73], v[54:55], v[172:173], v[86:87] op_sel_hi:[1,0,1]
	v_pk_fma_f32 v[66:67], v[52:53], v[172:173], v[84:85] op_sel_hi:[1,0,1]
	v_pk_fma_f32 v[68:69], v[50:51], v[172:173], v[82:83] op_sel_hi:[1,0,1]
	s_mov_b64 s[0:1], -1
	s_and_b64 vcc, exec, s[6:7]
	s_cbranch_vccz .LBB0_491
	v_pk_mul_f32 v[50:51], v[62:63], s[100:101]
	v_pk_mul_f32 v[54:55], v[58:59], s[100:101]
	v_pk_mul_f32 v[52:53], v[64:65], s[100:101]
	v_pk_mul_f32 v[56:57], v[60:61], s[100:101]
	v_exp_f32_e32 v50, v50
	v_exp_f32_e32 v51, v51
	v_exp_f32_e32 v54, v54
	v_exp_f32_e32 v55, v55
	v_exp_f32_e32 v52, v52
	v_exp_f32_e32 v53, v53
	v_exp_f32_e32 v56, v56
	v_exp_f32_e32 v57, v57
	v_pk_add_f32 v[50:51], v[50:51], 1.0 op_sel_hi:[1,0]
	v_pk_add_f32 v[54:55], v[54:55], 1.0 op_sel_hi:[1,0]
	v_pk_add_f32 v[52:53], v[52:53], 1.0 op_sel_hi:[1,0]
	v_pk_add_f32 v[56:57], v[56:57], 1.0 op_sel_hi:[1,0]
	v_rcp_f32_e32 v50, v50
	v_rcp_f32_e32 v51, v51
	v_rcp_f32_e32 v54, v54
	v_rcp_f32_e32 v55, v55
	v_rcp_f32_e32 v52, v52
	v_rcp_f32_e32 v53, v53
	v_rcp_f32_e32 v56, v56
	v_rcp_f32_e32 v57, v57
	v_pk_mul_f32 v[50:51], v[62:63], v[50:51]
	v_pk_mul_f32 v[54:55], v[58:59], v[54:55]
	v_pk_mul_f32 v[52:53], v[64:65], v[52:53]
	v_pk_mul_f32 v[56:57], v[60:61], v[56:57]
	v_pk_mul_f32 v[52:53], v[70:71], v[52:53]
	v_pk_mul_f32 v[50:51], v[72:73], v[50:51]
	v_pk_mul_f32 v[56:57], v[66:67], v[56:57]
	v_pk_mul_f32 v[54:55], v[68:69], v[54:55]
	s_mov_b64 s[0:1], 0

.LBB0_493:
	v_add_u32_e32 v58, 0x80, v138
	v_cvt_pk_bf16_f32 v50, v50, v51
	v_cvt_pk_bf16_f32 v51, v52, v53
	v_cvt_pk_bf16_f32 v52, v54, v55
	v_mad_i64_i32 v[54:55], s[0:1], s46, v58, 0
	v_cvt_pk_bf16_f32 v53, v56, v57
	v_lshl_add_u64 v[54:55], v[54:55], 1, v[168:169]
	global_store_dwordx4 v[54:55], v[50:53], off
	v_pk_fma_f32 v[48:49], v[48:49], v[170:171], v[96:97] op_sel_hi:[1,0,1]
	v_pk_fma_f32 v[46:47], v[46:47], v[170:171], v[94:95] op_sel_hi:[1,0,1]
	v_pk_fma_f32 v[44:45], v[44:45], v[170:171], v[92:93] op_sel_hi:[1,0,1]
	v_pk_fma_f32 v[42:43], v[42:43], v[170:171], v[90:91] op_sel_hi:[1,0,1]
	v_pk_fma_f32 v[54:55], v[40:41], v[170:171], v[88:89] op_sel_hi:[1,0,1]
	v_pk_fma_f32 v[56:57], v[38:39], v[170:171], v[86:87] op_sel_hi:[1,0,1]
	v_pk_fma_f32 v[50:51], v[36:37], v[170:171], v[84:85] op_sel_hi:[1,0,1]
	v_pk_fma_f32 v[52:53], v[34:35], v[170:171], v[82:83] op_sel_hi:[1,0,1]
	s_mov_b64 s[0:1], -1
	s_and_b64 vcc, exec, s[6:7]
	s_cbranch_vccz .LBB0_495
	v_pk_mul_f32 v[34:35], v[46:47], s[100:101]
	v_pk_mul_f32 v[38:39], v[42:43], s[100:101]
	v_pk_mul_f32 v[36:37], v[48:49], s[100:101]
	v_pk_mul_f32 v[40:41], v[44:45], s[100:101]
	v_exp_f32_e32 v34, v34
	v_exp_f32_e32 v35, v35
	v_exp_f32_e32 v38, v38
	v_exp_f32_e32 v39, v39
	v_exp_f32_e32 v36, v36
	v_exp_f32_e32 v37, v37
	v_exp_f32_e32 v40, v40
	v_exp_f32_e32 v41, v41
	v_pk_add_f32 v[34:35], v[34:35], 1.0 op_sel_hi:[1,0]
	v_pk_add_f32 v[38:39], v[38:39], 1.0 op_sel_hi:[1,0]
	v_pk_add_f32 v[36:37], v[36:37], 1.0 op_sel_hi:[1,0]
	v_pk_add_f32 v[40:41], v[40:41], 1.0 op_sel_hi:[1,0]
	v_rcp_f32_e32 v34, v34
	v_rcp_f32_e32 v35, v35
	v_rcp_f32_e32 v38, v38
	v_rcp_f32_e32 v39, v39
	v_rcp_f32_e32 v36, v36
	v_rcp_f32_e32 v37, v37
	v_rcp_f32_e32 v40, v40
	v_rcp_f32_e32 v41, v41
	v_pk_mul_f32 v[34:35], v[46:47], v[34:35]
	v_pk_mul_f32 v[38:39], v[42:43], v[38:39]
	v_pk_mul_f32 v[36:37], v[48:49], v[36:37]
	v_pk_mul_f32 v[40:41], v[44:45], v[40:41]
	v_pk_mul_f32 v[36:37], v[54:55], v[36:37]
	v_pk_mul_f32 v[34:35], v[56:57], v[34:35]
	v_pk_mul_f32 v[40:41], v[50:51], v[40:41]
	v_pk_mul_f32 v[38:39], v[52:53], v[38:39]
	s_mov_b64 s[0:1], 0

.LBB0_497:
	v_cvt_pk_bf16_f32 v34, v34, v35
	v_cvt_pk_bf16_f32 v35, v36, v37
	s_nop 0
	v_cvt_pk_bf16_f32 v36, v38, v39
	v_add_u32_e32 v38, 0x90, v138
	v_mad_i64_i32 v[38:39], s[0:1], s46, v38, 0
	v_cvt_pk_bf16_f32 v37, v40, v41
	v_lshl_add_u64 v[38:39], v[38:39], 1, v[168:169]
	global_store_dwordx4 v[38:39], v[34:37], off
	v_pk_fma_f32 v[32:33], v[32:33], v[166:167], v[96:97] op_sel_hi:[1,0,1]
	v_pk_fma_f32 v[30:31], v[30:31], v[166:167], v[94:95] op_sel_hi:[1,0,1]
	v_pk_fma_f32 v[28:29], v[28:29], v[166:167], v[92:93] op_sel_hi:[1,0,1]
	v_pk_fma_f32 v[26:27], v[26:27], v[166:167], v[90:91] op_sel_hi:[1,0,1]
	v_pk_fma_f32 v[38:39], v[24:25], v[166:167], v[88:89] op_sel_hi:[1,0,1]
	v_pk_fma_f32 v[40:41], v[22:23], v[166:167], v[86:87] op_sel_hi:[1,0,1]
	v_pk_fma_f32 v[34:35], v[20:21], v[166:167], v[84:85] op_sel_hi:[1,0,1]
	v_pk_fma_f32 v[36:37], v[18:19], v[166:167], v[82:83] op_sel_hi:[1,0,1]
	s_mov_b64 s[0:1], -1
	s_and_b64 vcc, exec, s[6:7]
	s_cbranch_vccz .LBB0_499
	v_pk_mul_f32 v[18:19], v[30:31], s[100:101]
	v_pk_mul_f32 v[22:23], v[26:27], s[100:101]
	v_pk_mul_f32 v[20:21], v[32:33], s[100:101]
	v_pk_mul_f32 v[24:25], v[28:29], s[100:101]
	v_exp_f32_e32 v18, v18
	v_exp_f32_e32 v19, v19
	v_exp_f32_e32 v22, v22
	v_exp_f32_e32 v23, v23
	v_exp_f32_e32 v20, v20
	v_exp_f32_e32 v21, v21
	v_exp_f32_e32 v24, v24
	v_exp_f32_e32 v25, v25
	v_pk_add_f32 v[18:19], v[18:19], 1.0 op_sel_hi:[1,0]
	v_pk_add_f32 v[22:23], v[22:23], 1.0 op_sel_hi:[1,0]
	v_pk_add_f32 v[20:21], v[20:21], 1.0 op_sel_hi:[1,0]
	v_pk_add_f32 v[24:25], v[24:25], 1.0 op_sel_hi:[1,0]
	v_rcp_f32_e32 v18, v18
	v_rcp_f32_e32 v19, v19
	v_rcp_f32_e32 v22, v22
	v_rcp_f32_e32 v23, v23
	v_rcp_f32_e32 v20, v20
	v_rcp_f32_e32 v21, v21
	v_rcp_f32_e32 v24, v24
	v_rcp_f32_e32 v25, v25
	v_pk_mul_f32 v[18:19], v[30:31], v[18:19]
	v_pk_mul_f32 v[22:23], v[26:27], v[22:23]
	v_pk_mul_f32 v[20:21], v[32:33], v[20:21]
	v_pk_mul_f32 v[24:25], v[28:29], v[24:25]
	v_pk_mul_f32 v[20:21], v[38:39], v[20:21]
	v_pk_mul_f32 v[18:19], v[40:41], v[18:19]
	v_pk_mul_f32 v[24:25], v[34:35], v[24:25]
	v_pk_mul_f32 v[22:23], v[36:37], v[22:23]
	s_mov_b64 s[0:1], 0

.LBB0_501:
	v_cvt_pk_bf16_f32 v18, v18, v19
	v_cvt_pk_bf16_f32 v19, v20, v21
	s_nop 0
	v_cvt_pk_bf16_f32 v20, v22, v23
	v_add_u32_e32 v22, 0xa0, v138
	v_mad_i64_i32 v[22:23], s[0:1], s46, v22, 0
	v_cvt_pk_bf16_f32 v21, v24, v25
	v_lshl_add_u64 v[22:23], v[22:23], 1, v[168:169]
	global_store_dwordx4 v[22:23], v[18:21], off
	v_pk_fma_f32 v[16:17], v[16:17], v[164:165], v[96:97] op_sel_hi:[1,0,1]
	v_pk_fma_f32 v[14:15], v[14:15], v[164:165], v[94:95] op_sel_hi:[1,0,1]
	v_pk_fma_f32 v[12:13], v[12:13], v[164:165], v[92:93] op_sel_hi:[1,0,1]
	v_pk_fma_f32 v[10:11], v[10:11], v[164:165], v[90:91] op_sel_hi:[1,0,1]
	v_pk_fma_f32 v[22:23], v[8:9], v[164:165], v[88:89] op_sel_hi:[1,0,1]
	v_pk_fma_f32 v[24:25], v[6:7], v[164:165], v[86:87] op_sel_hi:[1,0,1]
	v_pk_fma_f32 v[18:19], v[4:5], v[164:165], v[84:85] op_sel_hi:[1,0,1]
	v_pk_fma_f32 v[20:21], v[2:3], v[164:165], v[82:83] op_sel_hi:[1,0,1]
	s_mov_b64 s[0:1], -1
	s_and_b64 vcc, exec, s[6:7]
	s_cbranch_vccz .LBB0_503
	v_pk_mul_f32 v[2:3], v[14:15], s[100:101]
	v_pk_mul_f32 v[6:7], v[10:11], s[100:101]
	v_pk_mul_f32 v[4:5], v[16:17], s[100:101]
	v_pk_mul_f32 v[8:9], v[12:13], s[100:101]
	v_exp_f32_e32 v2, v2
	v_exp_f32_e32 v3, v3
	v_exp_f32_e32 v6, v6
	v_exp_f32_e32 v7, v7
	v_exp_f32_e32 v4, v4
	v_exp_f32_e32 v5, v5
	v_exp_f32_e32 v8, v8
	v_exp_f32_e32 v9, v9
	v_pk_add_f32 v[2:3], v[2:3], 1.0 op_sel_hi:[1,0]
	v_pk_add_f32 v[6:7], v[6:7], 1.0 op_sel_hi:[1,0]
	v_pk_add_f32 v[4:5], v[4:5], 1.0 op_sel_hi:[1,0]
	v_pk_add_f32 v[8:9], v[8:9], 1.0 op_sel_hi:[1,0]
	v_rcp_f32_e32 v2, v2
	v_rcp_f32_e32 v3, v3
	v_rcp_f32_e32 v6, v6
	v_rcp_f32_e32 v7, v7
	v_rcp_f32_e32 v4, v4
	v_rcp_f32_e32 v5, v5
	v_rcp_f32_e32 v8, v8
	v_rcp_f32_e32 v9, v9
	v_pk_mul_f32 v[2:3], v[14:15], v[2:3]
	v_pk_mul_f32 v[6:7], v[10:11], v[6:7]
	v_pk_mul_f32 v[4:5], v[16:17], v[4:5]
	v_pk_mul_f32 v[8:9], v[12:13], v[8:9]
	v_pk_mul_f32 v[4:5], v[22:23], v[4:5]
	v_pk_mul_f32 v[2:3], v[24:25], v[2:3]
	v_pk_mul_f32 v[8:9], v[18:19], v[8:9]
	v_pk_mul_f32 v[6:7], v[20:21], v[6:7]
	s_mov_b64 s[0:1], 0
